# P0 weight loads non-temporal (f32 weights are read exactly once)
# speedup vs baseline: 1.0037x; 1.0037x over previous
; __device__ __forceinline__ void p0_item(const float* W, int ldw, int col0, int k0, const float* gain, bf16_t* WT, int K, int drow0, LAS float* scr, int lane) {
;     ...
;     const float* src = W + (size_t)k0 * ldw + col0 + lane;
; #pragma unroll
;     for (int i = 0; i < 64; ++i) v[i] = src[(size_t)i * ldw];
.Lp0_rows:
	s_mul_i32 s4, s33, s30
	s_add_u32 s4, s4, s31
	s_lshl_b32 s4, s4, 2
	s_add_u32 s40, s28, s4
	s_addc_u32 s41, s29, 0
	s_lshl_b32 s5, s30, 2
	global_load_dword v2, v66, s[40:41] nt
	s_add_u32 s40, s40, s5
	s_addc_u32 s41, s41, 0
	global_load_dword v3, v66, s[40:41] nt
	s_add_u32 s40, s40, s5
	s_addc_u32 s41, s41, 0
	global_load_dword v4, v66, s[40:41] nt
	s_add_u32 s40, s40, s5
	s_addc_u32 s41, s41, 0
	global_load_dword v5, v66, s[40:41] nt
	s_add_u32 s40, s40, s5
	s_addc_u32 s41, s41, 0
	global_load_dword v6, v66, s[40:41] nt
	s_add_u32 s40, s40, s5
	s_addc_u32 s41, s41, 0
	global_load_dword v7, v66, s[40:41] nt
	s_add_u32 s40, s40, s5
	s_addc_u32 s41, s41, 0
	global_load_dword v8, v66, s[40:41] nt
	s_add_u32 s40, s40, s5
	s_addc_u32 s41, s41, 0
	global_load_dword v9, v66, s[40:41] nt
	s_add_u32 s40, s40, s5
	s_addc_u32 s41, s41, 0
	global_load_dword v10, v66, s[40:41] nt
	s_add_u32 s40, s40, s5
	s_addc_u32 s41, s41, 0
	global_load_dword v11, v66, s[40:41] nt
	s_add_u32 s40, s40, s5
	s_addc_u32 s41, s41, 0
	global_load_dword v12, v66, s[40:41] nt
	s_add_u32 s40, s40, s5
	s_addc_u32 s41, s41, 0
	global_load_dword v13, v66, s[40:41] nt
	s_add_u32 s40, s40, s5
	s_addc_u32 s41, s41, 0
	global_load_dword v14, v66, s[40:41] nt
	s_add_u32 s40, s40, s5
	s_addc_u32 s41, s41, 0
	global_load_dword v15, v66, s[40:41] nt
	s_add_u32 s40, s40, s5
	s_addc_u32 s41, s41, 0
	global_load_dword v16, v66, s[40:41] nt
	s_add_u32 s40, s40, s5
	s_addc_u32 s41, s41, 0
	global_load_dword v17, v66, s[40:41] nt
	s_add_u32 s40, s40, s5
	s_addc_u32 s41, s41, 0
	global_load_dword v18, v66, s[40:41] nt
	s_add_u32 s40, s40, s5
	s_addc_u32 s41, s41, 0
	global_load_dword v19, v66, s[40:41] nt
	s_add_u32 s40, s40, s5
	s_addc_u32 s41, s41, 0
	global_load_dword v20, v66, s[40:41] nt
	s_add_u32 s40, s40, s5
	s_addc_u32 s41, s41, 0
	global_load_dword v21, v66, s[40:41] nt
	s_add_u32 s40, s40, s5
	s_addc_u32 s41, s41, 0
	global_load_dword v22, v66, s[40:41] nt
	s_add_u32 s40, s40, s5
	s_addc_u32 s41, s41, 0
	global_load_dword v23, v66, s[40:41] nt
	s_add_u32 s40, s40, s5
	s_addc_u32 s41, s41, 0
	global_load_dword v24, v66, s[40:41] nt
	s_add_u32 s40, s40, s5
	s_addc_u32 s41, s41, 0
	global_load_dword v25, v66, s[40:41] nt
	s_add_u32 s40, s40, s5
	s_addc_u32 s41, s41, 0
	global_load_dword v26, v66, s[40:41] nt
	s_add_u32 s40, s40, s5
	s_addc_u32 s41, s41, 0
	global_load_dword v27, v66, s[40:41] nt
	s_add_u32 s40, s40, s5
	s_addc_u32 s41, s41, 0
	global_load_dword v28, v66, s[40:41] nt
	s_add_u32 s40, s40, s5
	s_addc_u32 s41, s41, 0
	global_load_dword v29, v66, s[40:41] nt
	s_add_u32 s40, s40, s5
	s_addc_u32 s41, s41, 0
	global_load_dword v30, v66, s[40:41] nt
	s_add_u32 s40, s40, s5
	s_addc_u32 s41, s41, 0
	global_load_dword v31, v66, s[40:41] nt
	s_add_u32 s40, s40, s5
	s_addc_u32 s41, s41, 0
	global_load_dword v32, v66, s[40:41] nt
	s_add_u32 s40, s40, s5
	s_addc_u32 s41, s41, 0
	global_load_dword v33, v66, s[40:41] nt
	s_add_u32 s40, s40, s5
	s_addc_u32 s41, s41, 0
	global_load_dword v34, v66, s[40:41] nt
	s_add_u32 s40, s40, s5
	s_addc_u32 s41, s41, 0
	global_load_dword v35, v66, s[40:41] nt
	s_add_u32 s40, s40, s5
	s_addc_u32 s41, s41, 0
	global_load_dword v36, v66, s[40:41] nt
	s_add_u32 s40, s40, s5
	s_addc_u32 s41, s41, 0
	global_load_dword v37, v66, s[40:41] nt
	s_add_u32 s40, s40, s5
	s_addc_u32 s41, s41, 0
	global_load_dword v38, v66, s[40:41] nt
	s_add_u32 s40, s40, s5
	s_addc_u32 s41, s41, 0
	global_load_dword v39, v66, s[40:41] nt
	s_add_u32 s40, s40, s5
	s_addc_u32 s41, s41, 0
	global_load_dword v40, v66, s[40:41] nt
	s_add_u32 s40, s40, s5
	s_addc_u32 s41, s41, 0
	global_load_dword v41, v66, s[40:41] nt
	s_add_u32 s40, s40, s5
	s_addc_u32 s41, s41, 0
	global_load_dword v42, v66, s[40:41] nt
	s_add_u32 s40, s40, s5
	s_addc_u32 s41, s41, 0
	global_load_dword v43, v66, s[40:41] nt
	s_add_u32 s40, s40, s5
	s_addc_u32 s41, s41, 0
	global_load_dword v44, v66, s[40:41] nt
	s_add_u32 s40, s40, s5
	s_addc_u32 s41, s41, 0
	global_load_dword v45, v66, s[40:41] nt
	s_add_u32 s40, s40, s5
	s_addc_u32 s41, s41, 0
	global_load_dword v46, v66, s[40:41] nt
	s_add_u32 s40, s40, s5
	s_addc_u32 s41, s41, 0
	global_load_dword v47, v66, s[40:41] nt
	s_add_u32 s40, s40, s5
	s_addc_u32 s41, s41, 0
	global_load_dword v48, v66, s[40:41] nt
	s_add_u32 s40, s40, s5
	s_addc_u32 s41, s41, 0
	global_load_dword v49, v66, s[40:41] nt
	s_add_u32 s40, s40, s5
	s_addc_u32 s41, s41, 0
	global_load_dword v50, v66, s[40:41] nt
	s_add_u32 s40, s40, s5
	s_addc_u32 s41, s41, 0
	global_load_dword v51, v66, s[40:41] nt
	s_add_u32 s40, s40, s5
	s_addc_u32 s41, s41, 0
	global_load_dword v52, v66, s[40:41] nt
	s_add_u32 s40, s40, s5
	s_addc_u32 s41, s41, 0
	global_load_dword v53, v66, s[40:41] nt
	s_add_u32 s40, s40, s5
	s_addc_u32 s41, s41, 0
	global_load_dword v54, v66, s[40:41] nt
	s_add_u32 s40, s40, s5
	s_addc_u32 s41, s41, 0
	global_load_dword v55, v66, s[40:41] nt
	s_add_u32 s40, s40, s5
	s_addc_u32 s41, s41, 0
	global_load_dword v56, v66, s[40:41] nt
	s_add_u32 s40, s40, s5
	s_addc_u32 s41, s41, 0
	global_load_dword v57, v66, s[40:41] nt
	s_add_u32 s40, s40, s5
	s_addc_u32 s41, s41, 0
	global_load_dword v58, v66, s[40:41] nt
	s_add_u32 s40, s40, s5
	s_addc_u32 s41, s41, 0
	global_load_dword v59, v66, s[40:41] nt
	s_add_u32 s40, s40, s5
	s_addc_u32 s41, s41, 0
	global_load_dword v60, v66, s[40:41] nt
	s_add_u32 s40, s40, s5
	s_addc_u32 s41, s41, 0
	global_load_dword v61, v66, s[40:41] nt
	s_add_u32 s40, s40, s5
	s_addc_u32 s41, s41, 0
	global_load_dword v62, v66, s[40:41] nt
	s_add_u32 s40, s40, s5
	s_addc_u32 s41, s41, 0
	global_load_dword v63, v66, s[40:41] nt
	s_add_u32 s40, s40, s5
	s_addc_u32 s41, s41, 0
	global_load_dword v64, v66, s[40:41] nt
	s_add_u32 s40, s40, s5
	s_addc_u32 s41, s41, 0
	global_load_dword v65, v66, s[40:41] nt
	s_mul_i32 s4, s39, s38
	s_add_u32 s4, s4, s33
	s_lshl_b32 s4, s4, 1
	s_add_u32 s44, s36, s4
	s_addc_u32 s45, s37, 0
	s_lshl_b32 s6, s38, 1
	v_mul_lo_u32 v78, v79, s6
	v_add_u32_e32 v78, v78, v92
	s_lshl_b32 s46, s38, 4
	s_waitcnt vmcnt(63)
; #define LAS __attribute__((address_space(3)))
; __device__ __forceinline__ unsigned cvtpk(float lo, float hi) { f32x2 v = {lo, hi}; bf16x2_t b = __builtin_convertvector(v, bf16x2_t); return __builtin_bit_cast(unsigned, b); }
; __device__ __forceinline__ void p0_item(const float* W, int ldw, int col0, int k0, const float* gain, bf16_t* WT, int K, int drow0, LAS float* scr, int lane) {
;     ...
;     for (int i = 0; i < 64; ++i) scr[i * 65 + lane] = v[i];
;     asm volatile("s_waitcnt lgkmcnt(0)" ::: "memory");
; #pragma unroll
;     for (int j = 0; j < 8; ++j) { const int n = (lane >> 3) + 8 * j; const LAS float* s = scr + (8 * c) * 65 + n;
;         u32x4 o; o.x = cvtpk(s[0 * 65] * g0[0], s[1 * 65] * g0[1]); o.y = cvtpk(s[2 * 65] * g0[2], s[3 * 65] * g0[3]); o.z = cvtpk(s[4 * 65] * g1[0], s[5 * 65] * g1[1]); o.w = cvtpk(s[6 * 65] * g1[2], s[7 * 65] * g1[3]);
	ds_write_b32 v76, v2 offset:0
	s_waitcnt vmcnt(62)
	ds_write_b32 v76, v3 offset:260
	s_waitcnt vmcnt(61)
	ds_write_b32 v76, v4 offset:520
	s_waitcnt vmcnt(60)
	ds_write_b32 v76, v5 offset:780
	s_waitcnt vmcnt(59)
	ds_write_b32 v76, v6 offset:1040
	s_waitcnt vmcnt(58)
	ds_write_b32 v76, v7 offset:1300
	s_waitcnt vmcnt(57)
	ds_write_b32 v76, v8 offset:1560
	s_waitcnt vmcnt(56)
	ds_write_b32 v76, v9 offset:1820
	s_waitcnt vmcnt(55)
	ds_write_b32 v76, v10 offset:2080
	s_waitcnt vmcnt(54)
	ds_write_b32 v76, v11 offset:2340
	s_waitcnt vmcnt(53)
	ds_write_b32 v76, v12 offset:2600
	s_waitcnt vmcnt(52)
	ds_write_b32 v76, v13 offset:2860
	s_waitcnt vmcnt(51)
	ds_write_b32 v76, v14 offset:3120
	s_waitcnt vmcnt(50)
	ds_write_b32 v76, v15 offset:3380
	s_waitcnt vmcnt(49)
	ds_write_b32 v76, v16 offset:3640
	s_waitcnt vmcnt(48)
	ds_write_b32 v76, v17 offset:3900
	s_waitcnt vmcnt(47)
	ds_write_b32 v76, v18 offset:4160
	s_waitcnt vmcnt(46)
	ds_write_b32 v76, v19 offset:4420
	s_waitcnt vmcnt(45)
	ds_write_b32 v76, v20 offset:4680
	s_waitcnt vmcnt(44)
	ds_write_b32 v76, v21 offset:4940
	s_waitcnt vmcnt(43)
	ds_write_b32 v76, v22 offset:5200
	s_waitcnt vmcnt(42)
	ds_write_b32 v76, v23 offset:5460
	s_waitcnt vmcnt(41)
	ds_write_b32 v76, v24 offset:5720
	s_waitcnt vmcnt(40)
	ds_write_b32 v76, v25 offset:5980
	s_waitcnt vmcnt(39)
	ds_write_b32 v76, v26 offset:6240
	s_waitcnt vmcnt(38)
	ds_write_b32 v76, v27 offset:6500
	s_waitcnt vmcnt(37)
	ds_write_b32 v76, v28 offset:6760
	s_waitcnt vmcnt(36)
	ds_write_b32 v76, v29 offset:7020
	s_waitcnt vmcnt(35)
	ds_write_b32 v76, v30 offset:7280
	s_waitcnt vmcnt(34)
	ds_write_b32 v76, v31 offset:7540
	s_waitcnt vmcnt(33)
	ds_write_b32 v76, v32 offset:7800
	s_waitcnt vmcnt(32)
	ds_write_b32 v76, v33 offset:8060
	s_waitcnt vmcnt(31)
	ds_write_b32 v76, v34 offset:8320
	s_waitcnt vmcnt(30)
	ds_write_b32 v76, v35 offset:8580
	s_waitcnt vmcnt(29)
	ds_write_b32 v76, v36 offset:8840
	s_waitcnt vmcnt(28)
	ds_write_b32 v76, v37 offset:9100
	s_waitcnt vmcnt(27)
	ds_write_b32 v76, v38 offset:9360
	s_waitcnt vmcnt(26)
	ds_write_b32 v76, v39 offset:9620
	s_waitcnt vmcnt(25)
	ds_write_b32 v76, v40 offset:9880
	s_waitcnt vmcnt(24)
	ds_write_b32 v76, v41 offset:10140
	s_waitcnt vmcnt(23)
	ds_write_b32 v76, v42 offset:10400
	s_waitcnt vmcnt(22)
	ds_write_b32 v76, v43 offset:10660
	s_waitcnt vmcnt(21)
	ds_write_b32 v76, v44 offset:10920
	s_waitcnt vmcnt(20)
	ds_write_b32 v76, v45 offset:11180
	s_waitcnt vmcnt(19)
	ds_write_b32 v76, v46 offset:11440
	s_waitcnt vmcnt(18)
	ds_write_b32 v76, v47 offset:11700
	s_waitcnt vmcnt(17)
	ds_write_b32 v76, v48 offset:11960
	s_waitcnt vmcnt(16)
	ds_write_b32 v76, v49 offset:12220
	s_waitcnt vmcnt(15)
	ds_write_b32 v76, v50 offset:12480
	s_waitcnt vmcnt(14)
	ds_write_b32 v76, v51 offset:12740
	s_waitcnt vmcnt(13)
	ds_write_b32 v76, v52 offset:13000
	s_waitcnt vmcnt(12)
	ds_write_b32 v76, v53 offset:13260
	s_waitcnt vmcnt(11)
	ds_write_b32 v76, v54 offset:13520
	s_waitcnt vmcnt(10)
	ds_write_b32 v76, v55 offset:13780
	s_waitcnt vmcnt(9)
	ds_write_b32 v76, v56 offset:14040
	s_waitcnt vmcnt(8)
	ds_write_b32 v76, v57 offset:14300
	s_waitcnt vmcnt(7)
	ds_write_b32 v76, v58 offset:14560
	s_waitcnt vmcnt(6)
	ds_write_b32 v76, v59 offset:14820
	s_waitcnt vmcnt(5)
	ds_write_b32 v76, v60 offset:15080
	s_waitcnt vmcnt(4)
	ds_write_b32 v76, v61 offset:15340
	s_waitcnt vmcnt(3)
	ds_write_b32 v76, v62 offset:15600
	s_waitcnt vmcnt(2)
	ds_write_b32 v76, v63 offset:15860
	s_waitcnt vmcnt(1)
	ds_write_b32 v76, v64 offset:16120
	s_waitcnt vmcnt(0)
	ds_write_b32 v76, v65 offset:16380
	s_waitcnt lgkmcnt(0)
	ds_read_b32 v80, v77 offset:0
	ds_read_b32 v81, v77 offset:260
	ds_read_b32 v82, v77 offset:520
	ds_read_b32 v83, v77 offset:780
	ds_read_b32 v84, v77 offset:1040
	ds_read_b32 v85, v77 offset:1300
	ds_read_b32 v86, v77 offset:1560
	ds_read_b32 v87, v77 offset:1820
	s_waitcnt lgkmcnt(0)
	v_pk_mul_f32 v[84:85], v[84:85], v[72:73]
	v_pk_mul_f32 v[86:87], v[86:87], v[74:75]
	v_pk_mul_f32 v[80:81], v[80:81], v[68:69]
	v_pk_mul_f32 v[82:83], v[82:83], v[70:71]
	v_cvt_pk_bf16_f32 v90, v84, v85
	v_cvt_pk_bf16_f32 v91, v86, v87
	v_cvt_pk_bf16_f32 v88, v80, v81
	v_cvt_pk_bf16_f32 v89, v82, v83
	ds_read_b32 v80, v77 offset:32
	ds_read_b32 v81, v77 offset:292
	ds_read_b32 v82, v77 offset:552
	ds_read_b32 v83, v77 offset:812
	ds_read_b32 v84, v77 offset:1072
	ds_read_b32 v85, v77 offset:1332
	ds_read_b32 v86, v77 offset:1592
	ds_read_b32 v87, v77 offset:1852
	global_store_dwordx4 v78, v[88:91], s[44:45]
	s_add_u32 s44, s44, s46
	s_addc_u32 s45, s45, 0
	s_waitcnt lgkmcnt(0)
; #define LAS __attribute__((address_space(3)))
; __device__ __forceinline__ unsigned cvtpk(float lo, float hi) { f32x2 v = {lo, hi}; bf16x2_t b = __builtin_convertvector(v, bf16x2_t); return __builtin_bit_cast(unsigned, b); }
; __device__ __forceinline__ void p0_item(const float* W, int ldw, int col0, int k0, const float* gain, bf16_t* WT, int K, int drow0, LAS float* scr, int lane) {
;     ...
;     for (int j = 0; j < 8; ++j) { const int n = (lane >> 3) + 8 * j; const LAS float* s = scr + (8 * c) * 65 + n;
;         u32x4 o; o.x = cvtpk(s[0 * 65] * g0[0], s[1 * 65] * g0[1]); o.y = cvtpk(s[2 * 65] * g0[2], s[3 * 65] * g0[3]); o.z = cvtpk(s[4 * 65] * g1[0], s[5 * 65] * g1[1]); o.w = cvtpk(s[6 * 65] * g1[2], s[7 * 65] * g1[3]);
;         *(u32x4*)(WT + (size_t)(drow0 + n) * K + k0 + 8 * c) = o; }
;     asm volatile("s_waitcnt lgkmcnt(0)" ::: "memory");
	v_pk_mul_f32 v[84:85], v[84:85], v[72:73]
	v_pk_mul_f32 v[86:87], v[86:87], v[74:75]
	v_pk_mul_f32 v[80:81], v[80:81], v[68:69]
	v_pk_mul_f32 v[82:83], v[82:83], v[70:71]
	v_cvt_pk_bf16_f32 v90, v84, v85
	v_cvt_pk_bf16_f32 v91, v86, v87
	v_cvt_pk_bf16_f32 v88, v80, v81
	v_cvt_pk_bf16_f32 v89, v82, v83
	ds_read_b32 v80, v77 offset:64
	ds_read_b32 v81, v77 offset:324
	ds_read_b32 v82, v77 offset:584
	ds_read_b32 v83, v77 offset:844
	ds_read_b32 v84, v77 offset:1104
	ds_read_b32 v85, v77 offset:1364
	ds_read_b32 v86, v77 offset:1624
	ds_read_b32 v87, v77 offset:1884
	global_store_dwordx4 v78, v[88:91], s[44:45]
	s_add_u32 s44, s44, s46
	s_addc_u32 s45, s45, 0
	s_waitcnt lgkmcnt(0)
	v_pk_mul_f32 v[84:85], v[84:85], v[72:73]
	v_pk_mul_f32 v[86:87], v[86:87], v[74:75]
	v_pk_mul_f32 v[80:81], v[80:81], v[68:69]
	v_pk_mul_f32 v[82:83], v[82:83], v[70:71]
	v_cvt_pk_bf16_f32 v90, v84, v85
	v_cvt_pk_bf16_f32 v91, v86, v87
	v_cvt_pk_bf16_f32 v88, v80, v81
	v_cvt_pk_bf16_f32 v89, v82, v83
	ds_read_b32 v80, v77 offset:96
	ds_read_b32 v81, v77 offset:356
	ds_read_b32 v82, v77 offset:616
	ds_read_b32 v83, v77 offset:876
	ds_read_b32 v84, v77 offset:1136
	ds_read_b32 v85, v77 offset:1396
	ds_read_b32 v86, v77 offset:1656
	ds_read_b32 v87, v77 offset:1916
	global_store_dwordx4 v78, v[88:91], s[44:45]
	s_add_u32 s44, s44, s46
	s_addc_u32 s45, s45, 0
	s_waitcnt lgkmcnt(0)
	v_pk_mul_f32 v[84:85], v[84:85], v[72:73]
	v_pk_mul_f32 v[86:87], v[86:87], v[74:75]
	v_pk_mul_f32 v[80:81], v[80:81], v[68:69]
	v_pk_mul_f32 v[82:83], v[82:83], v[70:71]
	v_cvt_pk_bf16_f32 v90, v84, v85
	v_cvt_pk_bf16_f32 v91, v86, v87
	v_cvt_pk_bf16_f32 v88, v80, v81
	v_cvt_pk_bf16_f32 v89, v82, v83
	ds_read_b32 v80, v77 offset:128
	ds_read_b32 v81, v77 offset:388
	ds_read_b32 v82, v77 offset:648
	ds_read_b32 v83, v77 offset:908
	ds_read_b32 v84, v77 offset:1168
	ds_read_b32 v85, v77 offset:1428
	ds_read_b32 v86, v77 offset:1688
	ds_read_b32 v87, v77 offset:1948
	global_store_dwordx4 v78, v[88:91], s[44:45]
	s_add_u32 s44, s44, s46
	s_addc_u32 s45, s45, 0
	s_waitcnt lgkmcnt(0)
	v_pk_mul_f32 v[84:85], v[84:85], v[72:73]
	v_pk_mul_f32 v[86:87], v[86:87], v[74:75]
	v_pk_mul_f32 v[80:81], v[80:81], v[68:69]
	v_pk_mul_f32 v[82:83], v[82:83], v[70:71]
	v_cvt_pk_bf16_f32 v90, v84, v85
	v_cvt_pk_bf16_f32 v91, v86, v87
	v_cvt_pk_bf16_f32 v88, v80, v81
	v_cvt_pk_bf16_f32 v89, v82, v83
	ds_read_b32 v80, v77 offset:160
	ds_read_b32 v81, v77 offset:420
	ds_read_b32 v82, v77 offset:680
	ds_read_b32 v83, v77 offset:940
	ds_read_b32 v84, v77 offset:1200
	ds_read_b32 v85, v77 offset:1460
	ds_read_b32 v86, v77 offset:1720
	ds_read_b32 v87, v77 offset:1980
	global_store_dwordx4 v78, v[88:91], s[44:45]
	s_add_u32 s44, s44, s46
	s_addc_u32 s45, s45, 0
	s_waitcnt lgkmcnt(0)
	v_pk_mul_f32 v[84:85], v[84:85], v[72:73]
	v_pk_mul_f32 v[86:87], v[86:87], v[74:75]
	v_pk_mul_f32 v[80:81], v[80:81], v[68:69]
	v_pk_mul_f32 v[82:83], v[82:83], v[70:71]
	v_cvt_pk_bf16_f32 v90, v84, v85
	v_cvt_pk_bf16_f32 v91, v86, v87
	v_cvt_pk_bf16_f32 v88, v80, v81
	v_cvt_pk_bf16_f32 v89, v82, v83
	ds_read_b32 v80, v77 offset:192
	ds_read_b32 v81, v77 offset:452
	ds_read_b32 v82, v77 offset:712
	ds_read_b32 v83, v77 offset:972
	ds_read_b32 v84, v77 offset:1232
	ds_read_b32 v85, v77 offset:1492
	ds_read_b32 v86, v77 offset:1752
	ds_read_b32 v87, v77 offset:2012
	global_store_dwordx4 v78, v[88:91], s[44:45]
	s_add_u32 s44, s44, s46
	s_addc_u32 s45, s45, 0
	s_waitcnt lgkmcnt(0)
	v_pk_mul_f32 v[84:85], v[84:85], v[72:73]
	v_pk_mul_f32 v[86:87], v[86:87], v[74:75]
	v_pk_mul_f32 v[80:81], v[80:81], v[68:69]
	v_pk_mul_f32 v[82:83], v[82:83], v[70:71]
	v_cvt_pk_bf16_f32 v90, v84, v85
	v_cvt_pk_bf16_f32 v91, v86, v87
	v_cvt_pk_bf16_f32 v88, v80, v81
	v_cvt_pk_bf16_f32 v89, v82, v83
	ds_read_b32 v80, v77 offset:224
	ds_read_b32 v81, v77 offset:484
	ds_read_b32 v82, v77 offset:744
	ds_read_b32 v83, v77 offset:1004
	ds_read_b32 v84, v77 offset:1264
	ds_read_b32 v85, v77 offset:1524
	ds_read_b32 v86, v77 offset:1784
	ds_read_b32 v87, v77 offset:2044
	global_store_dwordx4 v78, v[88:91], s[44:45]
	s_add_u32 s44, s44, s46
	s_addc_u32 s45, s45, 0
	s_waitcnt lgkmcnt(0)
	v_pk_mul_f32 v[84:85], v[84:85], v[72:73]
	v_pk_mul_f32 v[86:87], v[86:87], v[74:75]
	v_pk_mul_f32 v[80:81], v[80:81], v[68:69]
	v_pk_mul_f32 v[82:83], v[82:83], v[70:71]
	v_cvt_pk_bf16_f32 v90, v84, v85
	v_cvt_pk_bf16_f32 v91, v86, v87
	v_cvt_pk_bf16_f32 v88, v80, v81
	v_cvt_pk_bf16_f32 v89, v82, v83
	global_store_dwordx4 v78, v[88:91], s[44:45]
	s_add_i32 s55, s55, s1
	s_cmpk_gt_i32 s55, 0x567f
	s_cbranch_scc0 .Lp0_loop
